# G1 tile epilogue: the eight LDS->global copy chunks read together (dead fragment registers) and stored behind counted waits
# baseline (speedup 1.0000x reference)
.LBB0_262:
	v_cvt_pk_bf16_f32 v16, v148, v149
	v_cvt_pk_bf16_f32 v17, v150, v151
	v_cvt_pk_bf16_f32 v84, v84, v85
	v_cvt_pk_bf16_f32 v85, v86, v87
	v_cvt_pk_bf16_f32 v86, v136, v137
	v_cvt_pk_bf16_f32 v87, v138, v139
	v_cvt_pk_bf16_f32 v140, v144, v145
	v_cvt_pk_bf16_f32 v141, v146, v147
	ds_write2st64_b64 v219, v[16:17], v[86:87] offset0:64 offset1:72
	v_cvt_pk_bf16_f32 v16, v132, v133
	v_cvt_pk_bf16_f32 v17, v134, v135
	v_cvt_pk_bf16_f32 v88, v88, v89
	v_cvt_pk_bf16_f32 v89, v90, v91
	ds_write2st64_b64 v220, v[140:141], v[16:17] offset0:64 offset1:72
	v_cvt_pk_bf16_f32 v16, v96, v97
	v_cvt_pk_bf16_f32 v17, v98, v99
	ds_write2st64_b64 v221, v[88:89], v[16:17] offset0:64 offset1:72
	v_cvt_pk_bf16_f32 v16, v92, v93
	v_cvt_pk_bf16_f32 v17, v94, v95
	ds_write2st64_b64 v222, v[84:85], v[16:17] offset0:64 offset1:72
	v_cvt_pk_bf16_f32 v16, v128, v129
	v_cvt_pk_bf16_f32 v17, v130, v131
	v_cvt_pk_bf16_f32 v90, v120, v121
	v_cvt_pk_bf16_f32 v91, v122, v123
	v_cvt_pk_bf16_f32 v84, v124, v125
	v_cvt_pk_bf16_f32 v85, v126, v127
	ds_write2st64_b64 v219, v[16:17], v[90:91] offset0:80 offset1:88
	v_cvt_pk_bf16_f32 v16, v116, v117
	v_cvt_pk_bf16_f32 v17, v118, v119
	v_cvt_pk_bf16_f32 v86, v104, v105
	v_cvt_pk_bf16_f32 v87, v106, v107
	ds_write2st64_b64 v220, v[84:85], v[16:17] offset0:80 offset1:88
	v_cvt_pk_bf16_f32 v16, v112, v113
	v_cvt_pk_bf16_f32 v17, v114, v115
	v_cvt_pk_bf16_f32 v88, v100, v101
	v_cvt_pk_bf16_f32 v89, v102, v103
	ds_write2st64_b64 v221, v[86:87], v[16:17] offset0:80 offset1:88
	v_cvt_pk_bf16_f32 v16, v108, v109
	v_cvt_pk_bf16_f32 v17, v110, v111
	ds_write2st64_b64 v222, v[88:89], v[16:17] offset0:80 offset1:88
	v_or_b32_e32 v16, s80, v15
	s_movk_i32 s2, 0xd10
	v_cmp_gt_i32_e32 vcc, s2, v16
	s_waitcnt lgkmcnt(0)
	s_barrier
	s_and_saveexec_b64 s[2:3], vcc
	s_cbranch_execz .LBB0_177
	ds_read_b128 v[148:151], v223 offset:32768
	ds_read_b128 v[152:155], v224 offset:32768
	ds_read_b128 v[156:159], v225 offset:32768
	ds_read_b128 v[160:163], v226 offset:32768
	ds_read_b128 v[164:167], v227 offset:32768
	ds_read_b128 v[168:171], v228 offset:32768
	ds_read_b128 v[172:175], v229 offset:32768
	ds_read_b128 v[176:179], v230 offset:32768
	v_ashrrev_i32_e32 v17, 31, v16
	s_lshl_b32 s10, s12, 7
	v_lshl_add_u64 v[16:17], v[16:17], 1, s[4:5]
	v_add_u32_e32 v9, s10, v19
	v_mad_i64_i32 v[88:89], s[8:9], v9, s93, v[16:17]
	s_waitcnt lgkmcnt(7)
	global_store_dwordx4 v[88:89], v[148:151], off
	v_add_u32_e32 v9, s10, v190
	v_mad_i64_i32 v[88:89], s[8:9], v9, s93, v[16:17]
	v_add_u32_e32 v9, s10, v191
	s_waitcnt lgkmcnt(6)
	global_store_dwordx4 v[88:89], v[152:155], off
	v_mad_i64_i32 v[88:89], s[8:9], v9, s93, v[16:17]
	v_add_u32_e32 v9, s10, v199
	s_waitcnt lgkmcnt(5)
	global_store_dwordx4 v[88:89], v[156:159], off
	v_mad_i64_i32 v[88:89], s[8:9], v9, s93, v[16:17]
	v_add_u32_e32 v9, s10, v215
	s_waitcnt lgkmcnt(4)
	global_store_dwordx4 v[88:89], v[160:163], off
	v_mad_i64_i32 v[88:89], s[8:9], v9, s93, v[16:17]
	v_add_u32_e32 v9, s10, v216
	s_waitcnt lgkmcnt(3)
	global_store_dwordx4 v[88:89], v[164:167], off
	v_mad_i64_i32 v[88:89], s[8:9], v9, s93, v[16:17]
	v_add_u32_e32 v9, s10, v217
	s_waitcnt lgkmcnt(2)
	global_store_dwordx4 v[88:89], v[168:171], off
	v_mad_i64_i32 v[88:89], s[8:9], v9, s93, v[16:17]
	v_add_u32_e32 v9, s10, v218
	v_mad_i64_i32 v[16:17], s[8:9], v9, s93, v[16:17]
	s_waitcnt lgkmcnt(1)
	global_store_dwordx4 v[88:89], v[172:175], off
	s_waitcnt lgkmcnt(0)
	global_store_dwordx4 v[16:17], v[176:179], off
	s_branch .LBB0_177
